# GDN scan compute waves: loop hand-rewritten, LDS operand fragments prefetched 14 deep ahead of the MFMA chain, global_* loads/stores with counted vmcnt
# speedup vs baseline: 1.0094x; 1.0094x over previous
; #define MFMA16(a, b, c) __builtin_amdgcn_mfma_f32_16x16x32_bf16((a), (b), (c), 0, 0, 0)
; DI bf16x8 pack_tiles(const f32x4& a, const f32x4& b) { return pack8(a.x, a.y, a.z, a.w, b.x, b.y, b.z, b.w); }
; DI void gdn_scan_item(const Params& P, int l, int hh, int half, char* smem) {
;     ...
;     for (int n = 0; n < 256; ++n) {
;       const char* cb = smem + (n & 1) * SCAN_OPB;
;       const char* sWp = cb; const char* sQd = cb + 17408; const char* sKt = cb + 34816; const char* sQK = cb + 53248;
;       if (n + 1 < 256) { const size_t o8 = (size_t)(n + 1) * 8192;
; #pragma unroll
;         for (int it = 0; it < 4; ++it) un[it] = __builtin_nontemporal_load((const u32x2*)(Ut + o8 + uoff + 16 * it));
;         gn = gt[n + 1]; }
;       bf16x8 sb[4];
; #pragma unroll
;       for (int ks = 0; ks < 4; ++ks) sb[ks] = pack_tiles(St[2 * ks], St[2 * ks + 1]);
;       f32x4 wsv[4], qs[4];
; #pragma unroll
;       for (int it = 0; it < 4; ++it) { wsv[it] = (f32x4){0.f, 0.f, 0.f, 0.f}; qs[it] = (f32x4){0.f, 0.f, 0.f, 0.f}; }
; #pragma unroll
;       for (int it = 0; it < 4; ++it)
; #pragma unroll
;         for (int ks = 0; ks < 4; ++ks) { const int o = (16 * it + l15) * 272 + 64 * ks + 16 * q4;
;           const bf16x8 a = *(const bf16x8*)(sWp + o), a2 = *(const bf16x8*)(sQd + o);
;           wsv[it] = MFMA16(a, sb[ks], wsv[it]); qs[it] = MFMA16(a2, sb[ks], qs[it]); }
;     ...
;       for (int t = 0; t < 8; ++t) { St[t] *= gcur;
.LBB0_664:
	s_add_u32 s10, s10, 8
	s_addc_u32 s11, s11, 0
	s_addk_i32 s18, 0x80
	v_lshl_add_u64 v[72:73], v[72:73], 0, s[76:77]
	v_lshl_add_u64 v[74:75], v[74:75], 0, s[66:67]
	s_cmpk_eq_i32 s18, 0x4000
	v_lshl_add_u64 v[76:77], v[76:77], 0, s[66:67]
	s_cbranch_scc1 .LBB0_671
.LBB0_665:
	v_add_u32_e32 v204, v109, v111
	ds_read_b128 v[160:163], v110
	ds_read_b128 v[164:167], v110 offset:64
	ds_read_b128 v[168:171], v110 offset:128
	ds_read_b128 v[172:175], v110 offset:192
	ds_read_b128 v[176:179], v110 offset:4352
	ds_read_b128 v[180:183], v110 offset:4416
	ds_read_b128 v[184:187], v110 offset:4480
	ds_read_b128 v[188:191], v110 offset:4544
	ds_read_b128 v[192:195], v110 offset:8704
	ds_read_b128 v[196:199], v110 offset:8768
	ds_read_b128 v[200:203], v110 offset:8832
	ds_read_b128 v[212:215], v110 offset:8896
	ds_read_b128 v[216:219], v110 offset:13056
	ds_read_b128 v[220:223], v110 offset:13120
	v_cvt_pk_bf16_f32 v46, v14, v15
	v_cvt_pk_bf16_f32 v47, v16, v17
	v_cvt_pk_bf16_f32 v48, v30, v31
	v_cvt_pk_bf16_f32 v49, v32, v33
	v_cvt_pk_bf16_f32 v42, v26, v27
	v_cvt_pk_bf16_f32 v43, v28, v29
	v_cvt_pk_bf16_f32 v44, v22, v23
	v_cvt_pk_bf16_f32 v45, v24, v25
	v_cvt_pk_bf16_f32 v38, v18, v19
	v_cvt_pk_bf16_f32 v39, v20, v21
	v_cvt_pk_bf16_f32 v40, v10, v11
	v_cvt_pk_bf16_f32 v41, v12, v13
	v_cvt_pk_bf16_f32 v34, v6, v7
	v_cvt_pk_bf16_f32 v35, v8, v9
	v_cvt_pk_bf16_f32 v36, v2, v3
	v_cvt_pk_bf16_f32 v37, v4, v5
	s_cmp_lt_u32 s18, 0x100
	s_cbranch_scc1 .Lscan_wA0
	s_waitcnt vmcnt(3)
.Lscan_wA_back:
	v_lshl_add_u64 v[100:101], v[114:115], 0, v[72:73]
	v_add_co_u32_e32 v150, vcc, 0x282ec000, v100
	v_lshl_add_u64 v[98:99], v[114:115], 0, s[10:11]
	s_nop 0
	v_addc_co_u32_e32 v151, vcc, 0, v101, vcc
	global_load_dwordx2 v[96:97], v[150:151], off nt
	global_load_dwordx2 v[94:95], v[150:151], off offset:32 nt
	global_load_dwordx2 v[92:93], v[150:151], off offset:64 nt
	global_load_dwordx2 v[90:91], v[150:151], off offset:96 nt
	v_add_co_u32_e32 v154, vcc, s89, v98
	v_lshl_add_u64 v[104:105], v[114:115], 0, v[76:77]
	v_lshl_add_u64 v[102:103], v[114:115], 0, v[74:75]
	v_addc_co_u32_e32 v155, vcc, 0, v99, vcc
	global_load_dword v80, v[154:155], off offset:4
	v_add_u32_e32 v205, s18, v63
	s_waitcnt lgkmcnt(13)
	v_mfma_f32_16x16x32_bf16 v[120:123], v[160:163], v[46:49], 0
	ds_read_b128 v[160:163], v110 offset:13184
	v_pk_mul_f32 v[14:15], v[14:15], v[78:79] op_sel_hi:[1,0]
	s_waitcnt lgkmcnt(13)
	v_mfma_f32_16x16x32_bf16 v[120:123], v[164:167], v[42:45], v[120:123]
	ds_read_b128 v[164:167], v110 offset:13248
	v_pk_mul_f32 v[16:17], v[16:17], v[78:79] op_sel_hi:[1,0]
	s_waitcnt lgkmcnt(13)
	v_mfma_f32_16x16x32_bf16 v[120:123], v[168:171], v[38:41], v[120:123]
	ds_read_b128 v[168:171], v110 offset:17408
	v_pk_mul_f32 v[30:31], v[30:31], v[78:79] op_sel_hi:[1,0]
	s_waitcnt lgkmcnt(13)
	v_mfma_f32_16x16x32_bf16 v[120:123], v[172:175], v[34:37], v[120:123]
	ds_read_b128 v[172:175], v110 offset:17472
	v_pk_mul_f32 v[32:33], v[32:33], v[78:79] op_sel_hi:[1,0]
	s_waitcnt lgkmcnt(13)
	v_mfma_f32_16x16x32_bf16 v[124:127], v[176:179], v[46:49], 0
	ds_read_b128 v[176:179], v110 offset:17536
	v_pk_mul_f32 v[26:27], v[26:27], v[78:79] op_sel_hi:[1,0]
	s_waitcnt lgkmcnt(13)
	v_mfma_f32_16x16x32_bf16 v[124:127], v[180:183], v[42:45], v[124:127]
	ds_read_b128 v[180:183], v110 offset:17600
	v_pk_mul_f32 v[28:29], v[28:29], v[78:79] op_sel_hi:[1,0]
	s_waitcnt lgkmcnt(13)
	v_mfma_f32_16x16x32_bf16 v[124:127], v[184:187], v[38:41], v[124:127]
	ds_read_b128 v[184:187], v110 offset:21760
	v_pk_mul_f32 v[22:23], v[22:23], v[78:79] op_sel_hi:[1,0]
	s_waitcnt lgkmcnt(13)
	v_mfma_f32_16x16x32_bf16 v[124:127], v[188:191], v[34:37], v[124:127]
	ds_read_b128 v[188:191], v110 offset:21824
	v_pk_mul_f32 v[24:25], v[24:25], v[78:79] op_sel_hi:[1,0]
	s_waitcnt lgkmcnt(13)
	v_mfma_f32_16x16x32_bf16 v[128:131], v[192:195], v[46:49], 0
	ds_read_b128 v[192:195], v110 offset:21888
	v_pk_mul_f32 v[18:19], v[18:19], v[78:79] op_sel_hi:[1,0]
	s_waitcnt lgkmcnt(13)
	v_mfma_f32_16x16x32_bf16 v[128:131], v[196:199], v[42:45], v[128:131]
	ds_read_b128 v[196:199], v110 offset:21952
	v_pk_mul_f32 v[20:21], v[20:21], v[78:79] op_sel_hi:[1,0]
	s_waitcnt lgkmcnt(13)
	v_mfma_f32_16x16x32_bf16 v[128:131], v[200:203], v[38:41], v[128:131]
	ds_read_b128 v[200:203], v110 offset:26112
	v_pk_mul_f32 v[10:11], v[10:11], v[78:79] op_sel_hi:[1,0]
	s_waitcnt lgkmcnt(13)
	v_mfma_f32_16x16x32_bf16 v[128:131], v[212:215], v[34:37], v[128:131]
	ds_read_b128 v[212:215], v110 offset:26176
	v_pk_mul_f32 v[12:13], v[12:13], v[78:79] op_sel_hi:[1,0]
	s_waitcnt lgkmcnt(13)
	v_mfma_f32_16x16x32_bf16 v[132:135], v[216:219], v[46:49], 0
	ds_read_b128 v[216:219], v110 offset:26240
	v_pk_mul_f32 v[6:7], v[6:7], v[78:79] op_sel_hi:[1,0]
	s_waitcnt lgkmcnt(13)
	v_mfma_f32_16x16x32_bf16 v[132:135], v[220:223], v[42:45], v[132:135]
	ds_read_b128 v[220:223], v110 offset:26304
	v_pk_mul_f32 v[8:9], v[8:9], v[78:79] op_sel_hi:[1,0]
	s_waitcnt lgkmcnt(13)
	v_mfma_f32_16x16x32_bf16 v[132:135], v[160:163], v[38:41], v[132:135]
	ds_read_b128 v[160:163], v110 offset:30464
	v_pk_mul_f32 v[2:3], v[2:3], v[78:79] op_sel_hi:[1,0]
	s_waitcnt lgkmcnt(13)
	v_mfma_f32_16x16x32_bf16 v[132:135], v[164:167], v[34:37], v[132:135]
	ds_read_b128 v[164:167], v110 offset:30528
	v_pk_mul_f32 v[4:5], v[4:5], v[78:79] op_sel_hi:[1,0]
	s_waitcnt lgkmcnt(13)
	v_mfma_f32_16x16x32_bf16 v[50:53], v[168:171], v[46:49], 0
	ds_read_b128 v[168:171], v110 offset:30592
	v_lshlrev_b32_e32 v224, 16, v88
	v_and_b32_e32 v225, 0xffff0000, v88
	s_waitcnt lgkmcnt(13)
	v_mfma_f32_16x16x32_bf16 v[50:53], v[172:175], v[42:45], v[50:53]
	ds_read_b128 v[172:175], v110 offset:30656
	v_lshlrev_b32_e32 v226, 16, v89
	v_and_b32_e32 v227, 0xffff0000, v89
	s_waitcnt lgkmcnt(13)
; DI unsigned pack2(float lo, float hi) { f32x2 v = {lo, hi}; bf2_t b = __builtin_convertvector(v, bf2_t); return __builtin_bit_cast(unsigned, b); }
; DI float bflo(unsigned u) { return __uint_as_float(u << 16); }
; DI float bfhi(unsigned u) { return __uint_as_float(u & 0xffff0000u); }
; #define MFMA16(a, b, c) __builtin_amdgcn_mfma_f32_16x16x32_bf16((a), (b), (c), 0, 0, 0)
; DI bf16x8 pack_tiles(const f32x4& a, const f32x4& b) { return pack8(a.x, a.y, a.z, a.w, b.x, b.y, b.z, b.w); }
; DI void gdn_scan_item(const Params& P, int l, int hh, int half, char* smem) {
;     ...
;         for (int ks = 0; ks < 4; ++ks) { const int o = (16 * it + l15) * 272 + 64 * ks + 16 * q4;
;           const bf16x8 a = *(const bf16x8*)(sWp + o), a2 = *(const bf16x8*)(sQd + o);
;           wsv[it] = MFMA16(a, sb[ks], wsv[it]); qs[it] = MFMA16(a2, sb[ks], qs[it]); }
;       f32x4 vn[4];
; #pragma unroll
;       for (int it = 0; it < 4; ++it) { const f32x4 uf = {bflo(uc[it].x), bfhi(uc[it].x), bflo(uc[it].y), bfhi(uc[it].y)}; vn[it] = uf - wsv[it]; }
;       bf16x8 vb[2];
; #pragma unroll
;       for (int ks = 0; ks < 2; ++ks) vb[ks] = pack_tiles(vn[2 * ks], vn[2 * ks + 1]);
; #pragma unroll
;       for (int it = 0; it < 4; ++it)
; #pragma unroll
;         for (int ks = 0; ks < 2; ++ks) { const bf16x8 a = *(const bf16x8*)(sQK + (16 * it + l15) * 144 + 64 * ks + 16 * q4); qs[it] = MFMA16(a, vb[ks], qs[it]); }
;       { char* so = smem + SCAN_SO + (n & 1) * 8192 + (w * 4) * 512 + lane * 8;
; #pragma unroll
;         for (int it = 0; it < 4; ++it) { u32x2 ob = {pack2(qs[it].x, qs[it].y), pack2(qs[it].z, qs[it].w)}; *(u32x2*)(so + it * 512) = ob; } }
; #pragma unroll
;       for (int t = 0; t < 8; ++t) { St[t] *= gcur;
; #pragma unroll
;         for (int ks = 0; ks < 2; ++ks) { const bf16x8 a = *(const bf16x8*)(sKt + (16 * t + l15) * 144 + 64 * ks + 16 * q4); St[t] = MFMA16(a, vb[ks], St[t]); } }
	v_mfma_f32_16x16x32_bf16 v[50:53], v[176:179], v[38:41], v[50:53]
	ds_read_b128 v[176:179], v204 offset:53248
	v_lshlrev_b32_e32 v228, 16, v86
	v_and_b32_e32 v229, 0xffff0000, v86
	s_waitcnt lgkmcnt(13)
	v_mfma_f32_16x16x32_bf16 v[50:53], v[180:183], v[34:37], v[50:53]
	ds_read_b128 v[180:183], v204 offset:53312
	v_lshlrev_b32_e32 v230, 16, v87
	v_and_b32_e32 v231, 0xffff0000, v87
	s_waitcnt lgkmcnt(13)
	v_mfma_f32_16x16x32_bf16 v[54:57], v[184:187], v[46:49], 0
	ds_read_b128 v[184:187], v204 offset:55552
	v_lshlrev_b32_e32 v232, 16, v84
	v_and_b32_e32 v233, 0xffff0000, v84
	s_waitcnt lgkmcnt(13)
	v_mfma_f32_16x16x32_bf16 v[54:57], v[188:191], v[42:45], v[54:57]
	ds_read_b128 v[188:191], v204 offset:55616
	v_lshlrev_b32_e32 v234, 16, v85
	v_and_b32_e32 v235, 0xffff0000, v85
	s_waitcnt lgkmcnt(13)
	v_mfma_f32_16x16x32_bf16 v[54:57], v[192:195], v[38:41], v[54:57]
	ds_read_b128 v[192:195], v204 offset:57856
	v_lshlrev_b32_e32 v246, 16, v82
	v_and_b32_e32 v247, 0xffff0000, v82
	s_waitcnt lgkmcnt(13)
	v_mfma_f32_16x16x32_bf16 v[54:57], v[196:199], v[34:37], v[54:57]
	ds_read_b128 v[196:199], v204 offset:57920
	v_lshlrev_b32_e32 v248, 16, v83
	v_and_b32_e32 v249, 0xffff0000, v83
	s_waitcnt lgkmcnt(13)
	v_mfma_f32_16x16x32_bf16 v[58:61], v[200:203], v[46:49], 0
	ds_read_b128 v[200:203], v204 offset:60160
	v_sub_f32_e32 v224, v224, v120
	v_sub_f32_e32 v225, v225, v121
	v_sub_f32_e32 v226, v226, v122
	v_sub_f32_e32 v227, v227, v123
	s_waitcnt lgkmcnt(13)
	v_mfma_f32_16x16x32_bf16 v[58:61], v[212:215], v[42:45], v[58:61]
	ds_read_b128 v[212:215], v204 offset:60224
	v_sub_f32_e32 v228, v228, v124
	v_sub_f32_e32 v229, v229, v125
	v_sub_f32_e32 v230, v230, v126
	v_sub_f32_e32 v231, v231, v127
	s_waitcnt lgkmcnt(13)
	v_mfma_f32_16x16x32_bf16 v[58:61], v[216:219], v[38:41], v[58:61]
	ds_read_b128 v[216:219], v204 offset:34816
	v_sub_f32_e32 v232, v232, v128
	v_sub_f32_e32 v233, v233, v129
	v_sub_f32_e32 v234, v234, v130
	v_sub_f32_e32 v235, v235, v131
	s_waitcnt lgkmcnt(13)
	v_mfma_f32_16x16x32_bf16 v[58:61], v[220:223], v[34:37], v[58:61]
	ds_read_b128 v[220:223], v204 offset:34880
	v_sub_f32_e32 v246, v246, v132
	v_sub_f32_e32 v247, v247, v133
	v_sub_f32_e32 v248, v248, v134
	v_sub_f32_e32 v249, v249, v135
	s_waitcnt lgkmcnt(13)
	v_mfma_f32_16x16x32_bf16 v[136:139], v[160:163], v[46:49], 0
	ds_read_b128 v[160:163], v204 offset:37120
	v_cvt_pk_bf16_f32 v140, v224, v225
	v_cvt_pk_bf16_f32 v141, v226, v227
	s_waitcnt lgkmcnt(13)
	v_mfma_f32_16x16x32_bf16 v[136:139], v[164:167], v[42:45], v[136:139]
	ds_read_b128 v[164:167], v204 offset:37184
	v_cvt_pk_bf16_f32 v142, v228, v229
	v_cvt_pk_bf16_f32 v143, v230, v231
	s_waitcnt lgkmcnt(13)
	v_mfma_f32_16x16x32_bf16 v[136:139], v[168:171], v[38:41], v[136:139]
	ds_read_b128 v[168:171], v204 offset:39424
	v_cvt_pk_bf16_f32 v144, v232, v233
	v_cvt_pk_bf16_f32 v145, v234, v235
	s_waitcnt lgkmcnt(13)
	v_mfma_f32_16x16x32_bf16 v[136:139], v[172:175], v[34:37], v[136:139]
	ds_read_b128 v[172:175], v204 offset:39488
	v_cvt_pk_bf16_f32 v146, v246, v247
	v_cvt_pk_bf16_f32 v147, v248, v249
	s_waitcnt lgkmcnt(13)
	v_mfma_f32_16x16x32_bf16 v[50:53], v[176:179], v[140:143], v[50:53]
	ds_read_b128 v[176:179], v204 offset:41728
	s_waitcnt lgkmcnt(13)
	v_mfma_f32_16x16x32_bf16 v[50:53], v[180:183], v[144:147], v[50:53]
	ds_read_b128 v[180:183], v204 offset:41792
	s_waitcnt lgkmcnt(13)
	v_mfma_f32_16x16x32_bf16 v[54:57], v[184:187], v[140:143], v[54:57]
	ds_read_b128 v[184:187], v204 offset:44032
	s_waitcnt lgkmcnt(13)
	v_mfma_f32_16x16x32_bf16 v[54:57], v[188:191], v[144:147], v[54:57]
	ds_read_b128 v[188:191], v204 offset:44096
	s_waitcnt lgkmcnt(13)
	v_mfma_f32_16x16x32_bf16 v[58:61], v[192:195], v[140:143], v[58:61]
	ds_read_b128 v[192:195], v204 offset:46336
	s_waitcnt lgkmcnt(13)
	v_mfma_f32_16x16x32_bf16 v[58:61], v[196:199], v[144:147], v[58:61]
	ds_read_b128 v[196:199], v204 offset:46400
	s_waitcnt lgkmcnt(13)
	v_mfma_f32_16x16x32_bf16 v[136:139], v[200:203], v[140:143], v[136:139]
	ds_read_b128 v[200:203], v204 offset:48640
	s_waitcnt lgkmcnt(13)
	v_mfma_f32_16x16x32_bf16 v[136:139], v[212:215], v[144:147], v[136:139]
	ds_read_b128 v[212:215], v204 offset:48704
	s_waitcnt lgkmcnt(13)
	v_mfma_f32_16x16x32_bf16 v[14:17], v[216:219], v[140:143], v[14:17]
	ds_read_b128 v[216:219], v204 offset:50944
	s_waitcnt lgkmcnt(13)
	v_mfma_f32_16x16x32_bf16 v[14:17], v[220:223], v[144:147], v[14:17]
	ds_read_b128 v[220:223], v204 offset:51008
	s_cmp_eq_u32 s18, 0
	s_cbranch_scc1 .Lscan_cp1skipA
	v_add_u32_e32 v0, v108, v107
	ds_read_b128 v[224:227], v0
	v_add_u32_e32 v0, v108, v106
	ds_read_b128 v[228:231], v0
	ds_read_b32 v232, v81
; DI unsigned pack2(float lo, float hi) { f32x2 v = {lo, hi}; bf2_t b = __builtin_convertvector(v, bf2_t); return __builtin_bit_cast(unsigned, b); }
; #define MFMA16(a, b, c) __builtin_amdgcn_mfma_f32_16x16x32_bf16((a), (b), (c), 0, 0, 0)
; DI bf16x8 pack_tiles(const f32x4& a, const f32x4& b) { return pack8(a.x, a.y, a.z, a.w, b.x, b.y, b.z, b.w); }
; DI void gdn_scan_item(const Params& P, int l, int hh, int half, char* smem) {
;     ...
;     for (int n = 0; n < 256; ++n) {
;       const char* cb = smem + (n & 1) * SCAN_OPB;
;       const char* sWp = cb; const char* sQd = cb + 17408; const char* sKt = cb + 34816; const char* sQK = cb + 53248;
;       if (n + 1 < 256) { const size_t o8 = (size_t)(n + 1) * 8192;
; #pragma unroll
;         for (int it = 0; it < 4; ++it) un[it] = __builtin_nontemporal_load((const u32x2*)(Ut + o8 + uoff + 16 * it));
;         gn = gt[n + 1]; }
;       bf16x8 sb[4];
; #pragma unroll
;       for (int ks = 0; ks < 4; ++ks) sb[ks] = pack_tiles(St[2 * ks], St[2 * ks + 1]);
;       f32x4 wsv[4], qs[4];
; #pragma unroll
;       for (int it = 0; it < 4; ++it) { wsv[it] = (f32x4){0.f, 0.f, 0.f, 0.f}; qs[it] = (f32x4){0.f, 0.f, 0.f, 0.f}; }
; #pragma unroll
;       for (int it = 0; it < 4; ++it)
; #pragma unroll
;         for (int ks = 0; ks < 4; ++ks) { const int o = (16 * it + l15) * 272 + 64 * ks + 16 * q4;
;           const bf16x8 a = *(const bf16x8*)(sWp + o), a2 = *(const bf16x8*)(sQd + o);
;           wsv[it] = MFMA16(a, sb[ks], wsv[it]); qs[it] = MFMA16(a2, sb[ks], qs[it]); }
;     ...
;       for (int it = 0; it < 4; ++it)
; #pragma unroll
;         for (int ks = 0; ks < 2; ++ks) { const bf16x8 a = *(const bf16x8*)(sQK + (16 * it + l15) * 144 + 64 * ks + 16 * q4); qs[it] = MFMA16(a, vb[ks], qs[it]); }
;       { char* so = smem + SCAN_SO + (n & 1) * 8192 + (w * 4) * 512 + lane * 8;
; #pragma unroll
;         for (int it = 0; it < 4; ++it) { u32x2 ob = {pack2(qs[it].x, qs[it].y), pack2(qs[it].z, qs[it].w)}; *(u32x2*)(so + it * 512) = ob; } }
; #pragma unroll
;       for (int t = 0; t < 8; ++t) { St[t] *= gcur;
; #pragma unroll
;         for (int ks = 0; ks < 2; ++ks) { const bf16x8 a = *(const bf16x8*)(sKt + (16 * t + l15) * 144 + 64 * ks + 16 * q4); St[t] = MFMA16(a, vb[ks], St[t]); } }
; #pragma unroll
;       for (int it = 0; it < 4; ++it) uc[it] = un[it];
;       gcur = gn;
;       if (n >= 2) CP_OUT(n - 2);
;       __syncthreads();
;     }
.Lscan_cp1skipA:
	s_waitcnt lgkmcnt(13)
	v_mfma_f32_16x16x32_bf16 v[30:33], v[160:163], v[140:143], v[30:33]
	s_waitcnt lgkmcnt(12)
	v_mfma_f32_16x16x32_bf16 v[30:33], v[164:167], v[144:147], v[30:33]
	s_waitcnt lgkmcnt(11)
	v_mfma_f32_16x16x32_bf16 v[26:29], v[168:171], v[140:143], v[26:29]
	v_cvt_pk_bf16_f32 v236, v50, v51
	v_cvt_pk_bf16_f32 v237, v52, v53
	s_waitcnt lgkmcnt(10)
	v_mfma_f32_16x16x32_bf16 v[26:29], v[172:175], v[144:147], v[26:29]
	v_cvt_pk_bf16_f32 v210, v54, v55
	v_cvt_pk_bf16_f32 v211, v56, v57
	ds_write2st64_b64 v119, v[236:237], v[210:211] offset0:0 offset1:1
	s_waitcnt lgkmcnt(10)
	v_mfma_f32_16x16x32_bf16 v[22:25], v[176:179], v[140:143], v[22:25]
	s_waitcnt lgkmcnt(9)
	v_mfma_f32_16x16x32_bf16 v[22:25], v[180:183], v[144:147], v[22:25]
	s_waitcnt lgkmcnt(8)
	v_mfma_f32_16x16x32_bf16 v[18:21], v[184:187], v[140:143], v[18:21]
	v_cvt_pk_bf16_f32 v250, v58, v59
	v_cvt_pk_bf16_f32 v251, v60, v61
	s_waitcnt lgkmcnt(7)
	v_mfma_f32_16x16x32_bf16 v[18:21], v[188:191], v[144:147], v[18:21]
	v_cvt_pk_bf16_f32 v252, v136, v137
	v_cvt_pk_bf16_f32 v253, v138, v139
	ds_write2st64_b64 v119, v[250:251], v[252:253] offset0:2 offset1:3
	s_waitcnt lgkmcnt(7)
	v_mfma_f32_16x16x32_bf16 v[10:13], v[192:195], v[140:143], v[10:13]
	s_waitcnt lgkmcnt(6)
	v_mfma_f32_16x16x32_bf16 v[10:13], v[196:199], v[144:147], v[10:13]
	s_waitcnt lgkmcnt(5)
	v_mfma_f32_16x16x32_bf16 v[6:9], v[200:203], v[140:143], v[6:9]
	s_waitcnt lgkmcnt(4)
	v_mfma_f32_16x16x32_bf16 v[6:9], v[212:215], v[144:147], v[6:9]
	s_cmp_eq_u32 s18, 0
	s_cbranch_scc1 .Lscan_cp2skipA
	v_add_co_u32_e32 v150, vcc, 0x6268000, v104
	v_add_u32_e32 v0, 0xffffff80, v205
	v_lshlrev_b64 v[234:235], 5, v[0:1]
	v_addc_co_u32_e32 v151, vcc, 0, v105, vcc
	v_add_co_u32_e32 v154, vcc, 0x6268000, v102
	v_lshl_add_u64 v[234:235], v[70:71], 0, v[234:235]
	s_waitcnt lgkmcnt(2)
	v_addc_co_u32_e32 v155, vcc, 0, v103, vcc
	global_store_dwordx4 v[150:151], v[224:227], off
	global_store_dwordx4 v[154:155], v[228:231], off
	global_store_dword v[234:235], v232, off
.Lscan_cp2skipA:
	s_waitcnt lgkmcnt(3)
	v_mfma_f32_16x16x32_bf16 v[2:5], v[216:219], v[140:143], v[2:5]
	s_waitcnt lgkmcnt(2)
	v_mfma_f32_16x16x32_bf16 v[2:5], v[220:223], v[144:147], v[2:5]
	s_waitcnt lgkmcnt(0)
	s_barrier
	v_add_u32_e32 v204, 0x13800, v110
	ds_read_b128 v[160:163], v110 offset:62464
	ds_read_b128 v[164:167], v110 offset:62528
	ds_read_b128 v[168:171], v110 offset:62592
	ds_read_b128 v[172:175], v110 offset:62656
	ds_read_b128 v[176:179], v112 offset:62464
	ds_read_b128 v[180:183], v112 offset:62528
	ds_read_b128 v[184:187], v112 offset:62592
	ds_read_b128 v[188:191], v112 offset:62656
	ds_read_b128 v[192:195], v113 offset:62464
	ds_read_b128 v[196:199], v113 offset:62528
	ds_read_b128 v[200:203], v113 offset:62592
	ds_read_b128 v[212:215], v113 offset:62656
	ds_read_b128 v[216:219], v116 offset:62464
	ds_read_b128 v[220:223], v116 offset:62528
	v_cvt_pk_bf16_f32 v46, v14, v15
	v_cvt_pk_bf16_f32 v47, v16, v17
	v_cvt_pk_bf16_f32 v48, v30, v31
	v_cvt_pk_bf16_f32 v49, v32, v33
	v_cvt_pk_bf16_f32 v42, v26, v27
	v_cvt_pk_bf16_f32 v43, v28, v29
	v_cvt_pk_bf16_f32 v44, v22, v23
	v_cvt_pk_bf16_f32 v45, v24, v25
	v_cvt_pk_bf16_f32 v38, v18, v19
	v_cvt_pk_bf16_f32 v39, v20, v21
	v_cvt_pk_bf16_f32 v40, v10, v11
	v_cvt_pk_bf16_f32 v41, v12, v13
	v_cvt_pk_bf16_f32 v34, v6, v7
	v_cvt_pk_bf16_f32 v35, v8, v9
	v_cvt_pk_bf16_f32 v36, v2, v3
	v_cvt_pk_bf16_f32 v37, v4, v5
	s_cmp_eq_u32 s18, 0
	s_cbranch_scc1 .Lscan_wB0
	s_waitcnt vmcnt(3)
.Lscan_wB_back:
	s_cmpk_eq_i32 s18, 0x3f80
	s_cbranch_scc1 .Lscan_skipB
	v_add_co_u32_e32 v150, vcc, 0x282f0000, v100
	s_nop 1
	v_addc_co_u32_e32 v151, vcc, 0, v101, vcc
	global_load_dwordx2 v[88:89], v[150:151], off nt
	global_load_dwordx2 v[86:87], v[150:151], off offset:32 nt
	global_load_dwordx2 v[84:85], v[150:151], off offset:64 nt
	global_load_dwordx2 v[82:83], v[150:151], off offset:96 nt
	v_add_co_u32_e32 v154, vcc, 0x263e8000, v98
	s_nop 1
	v_addc_co_u32_e32 v155, vcc, 0, v99, vcc
	global_load_dword v78, v[154:155], off offset:8
.Lscan_skipB:
	s_waitcnt lgkmcnt(13)
	v_mfma_f32_16x16x32_bf16 v[120:123], v[160:163], v[46:49], 0
	ds_read_b128 v[160:163], v116 offset:62592
	v_pk_mul_f32 v[14:15], v[14:15], v[80:81] op_sel_hi:[1,0]
	s_waitcnt lgkmcnt(13)
	v_mfma_f32_16x16x32_bf16 v[120:123], v[164:167], v[42:45], v[120:123]
	ds_read_b128 v[164:167], v116 offset:62656
	v_pk_mul_f32 v[16:17], v[16:17], v[80:81] op_sel_hi:[1,0]
	s_waitcnt lgkmcnt(13)
	v_mfma_f32_16x16x32_bf16 v[120:123], v[168:171], v[38:41], v[120:123]
	ds_read_b128 v[168:171], v204
	v_pk_mul_f32 v[30:31], v[30:31], v[80:81] op_sel_hi:[1,0]
	s_waitcnt lgkmcnt(13)
	v_mfma_f32_16x16x32_bf16 v[120:123], v[172:175], v[34:37], v[120:123]
	ds_read_b128 v[172:175], v204 offset:64
	v_pk_mul_f32 v[32:33], v[32:33], v[80:81] op_sel_hi:[1,0]
	s_waitcnt lgkmcnt(13)
	v_mfma_f32_16x16x32_bf16 v[124:127], v[176:179], v[46:49], 0
	ds_read_b128 v[176:179], v204 offset:128
	v_pk_mul_f32 v[26:27], v[26:27], v[80:81] op_sel_hi:[1,0]
	s_waitcnt lgkmcnt(13)
	v_mfma_f32_16x16x32_bf16 v[124:127], v[180:183], v[42:45], v[124:127]
	ds_read_b128 v[180:183], v204 offset:192
	v_pk_mul_f32 v[28:29], v[28:29], v[80:81] op_sel_hi:[1,0]
	s_waitcnt lgkmcnt(13)
	v_mfma_f32_16x16x32_bf16 v[124:127], v[184:187], v[38:41], v[124:127]
	ds_read_b128 v[184:187], v204 offset:4352
	v_pk_mul_f32 v[22:23], v[22:23], v[80:81] op_sel_hi:[1,0]
	s_waitcnt lgkmcnt(13)
	v_mfma_f32_16x16x32_bf16 v[124:127], v[188:191], v[34:37], v[124:127]
	ds_read_b128 v[188:191], v204 offset:4416
	v_pk_mul_f32 v[24:25], v[24:25], v[80:81] op_sel_hi:[1,0]
	s_waitcnt lgkmcnt(13)
; DI unsigned pack2(float lo, float hi) { f32x2 v = {lo, hi}; bf2_t b = __builtin_convertvector(v, bf2_t); return __builtin_bit_cast(unsigned, b); }
; DI float bflo(unsigned u) { return __uint_as_float(u << 16); }
; DI float bfhi(unsigned u) { return __uint_as_float(u & 0xffff0000u); }
; #define MFMA16(a, b, c) __builtin_amdgcn_mfma_f32_16x16x32_bf16((a), (b), (c), 0, 0, 0)
; DI bf16x8 pack_tiles(const f32x4& a, const f32x4& b) { return pack8(a.x, a.y, a.z, a.w, b.x, b.y, b.z, b.w); }
; DI void gdn_scan_item(const Params& P, int l, int hh, int half, char* smem) {
;     ...
; #pragma unroll
;       for (int it = 0; it < 4; ++it)
; #pragma unroll
;         for (int ks = 0; ks < 4; ++ks) { const int o = (16 * it + l15) * 272 + 64 * ks + 16 * q4;
;           const bf16x8 a = *(const bf16x8*)(sWp + o), a2 = *(const bf16x8*)(sQd + o);
;           wsv[it] = MFMA16(a, sb[ks], wsv[it]); qs[it] = MFMA16(a2, sb[ks], qs[it]); }
;       f32x4 vn[4];
; #pragma unroll
;       for (int it = 0; it < 4; ++it) { const f32x4 uf = {bflo(uc[it].x), bfhi(uc[it].x), bflo(uc[it].y), bfhi(uc[it].y)}; vn[it] = uf - wsv[it]; }
;       bf16x8 vb[2];
; #pragma unroll
;       for (int ks = 0; ks < 2; ++ks) vb[ks] = pack_tiles(vn[2 * ks], vn[2 * ks + 1]);
; #pragma unroll
;       for (int it = 0; it < 4; ++it)
; #pragma unroll
;         for (int ks = 0; ks < 2; ++ks) { const bf16x8 a = *(const bf16x8*)(sQK + (16 * it + l15) * 144 + 64 * ks + 16 * q4); qs[it] = MFMA16(a, vb[ks], qs[it]); }
;       { char* so = smem + SCAN_SO + (n & 1) * 8192 + (w * 4) * 512 + lane * 8;
; #pragma unroll
;         for (int it = 0; it < 4; ++it) { u32x2 ob = {pack2(qs[it].x, qs[it].y), pack2(qs[it].z, qs[it].w)}; *(u32x2*)(so + it * 512) = ob; } }
; #pragma unroll
;       for (int t = 0; t < 8; ++t) { St[t] *= gcur;
; #pragma unroll
;         for (int ks = 0; ks < 2; ++ks) { const bf16x8 a = *(const bf16x8*)(sKt + (16 * t + l15) * 144 + 64 * ks + 16 * q4); St[t] = MFMA16(a, vb[ks], St[t]); } }
	v_mfma_f32_16x16x32_bf16 v[128:131], v[192:195], v[46:49], 0
	ds_read_b128 v[192:195], v204 offset:4480
	v_pk_mul_f32 v[18:19], v[18:19], v[80:81] op_sel_hi:[1,0]
	s_waitcnt lgkmcnt(13)
	v_mfma_f32_16x16x32_bf16 v[128:131], v[196:199], v[42:45], v[128:131]
	ds_read_b128 v[196:199], v204 offset:4544
	v_pk_mul_f32 v[20:21], v[20:21], v[80:81] op_sel_hi:[1,0]
	s_waitcnt lgkmcnt(13)
	v_mfma_f32_16x16x32_bf16 v[128:131], v[200:203], v[38:41], v[128:131]
	ds_read_b128 v[200:203], v204 offset:8704
	v_pk_mul_f32 v[10:11], v[10:11], v[80:81] op_sel_hi:[1,0]
	s_waitcnt lgkmcnt(13)
	v_mfma_f32_16x16x32_bf16 v[128:131], v[212:215], v[34:37], v[128:131]
	ds_read_b128 v[212:215], v204 offset:8768
	v_pk_mul_f32 v[12:13], v[12:13], v[80:81] op_sel_hi:[1,0]
	s_waitcnt lgkmcnt(13)
	v_mfma_f32_16x16x32_bf16 v[132:135], v[216:219], v[46:49], 0
	ds_read_b128 v[216:219], v204 offset:8832
	v_pk_mul_f32 v[6:7], v[6:7], v[80:81] op_sel_hi:[1,0]
	s_waitcnt lgkmcnt(13)
	v_mfma_f32_16x16x32_bf16 v[132:135], v[220:223], v[42:45], v[132:135]
	ds_read_b128 v[220:223], v204 offset:8896
	v_pk_mul_f32 v[8:9], v[8:9], v[80:81] op_sel_hi:[1,0]
	s_waitcnt lgkmcnt(13)
	v_mfma_f32_16x16x32_bf16 v[132:135], v[160:163], v[38:41], v[132:135]
	ds_read_b128 v[160:163], v204 offset:13056
	v_pk_mul_f32 v[2:3], v[2:3], v[80:81] op_sel_hi:[1,0]
	s_waitcnt lgkmcnt(13)
	v_mfma_f32_16x16x32_bf16 v[132:135], v[164:167], v[34:37], v[132:135]
	ds_read_b128 v[164:167], v204 offset:13120
	v_pk_mul_f32 v[4:5], v[4:5], v[80:81] op_sel_hi:[1,0]
	s_waitcnt lgkmcnt(13)
	v_mfma_f32_16x16x32_bf16 v[50:53], v[168:171], v[46:49], 0
	ds_read_b128 v[168:171], v204 offset:13184
	v_lshlrev_b32_e32 v224, 16, v96
	v_and_b32_e32 v225, 0xffff0000, v96
	s_waitcnt lgkmcnt(13)
	v_mfma_f32_16x16x32_bf16 v[50:53], v[172:175], v[42:45], v[50:53]
	ds_read_b128 v[172:175], v204 offset:13248
	v_lshlrev_b32_e32 v226, 16, v97
	v_and_b32_e32 v227, 0xffff0000, v97
	s_waitcnt lgkmcnt(13)
	v_mfma_f32_16x16x32_bf16 v[50:53], v[176:179], v[38:41], v[50:53]
	ds_read_b128 v[176:179], v117
	v_lshlrev_b32_e32 v228, 16, v94
	v_and_b32_e32 v229, 0xffff0000, v94
	s_waitcnt lgkmcnt(13)
	v_mfma_f32_16x16x32_bf16 v[50:53], v[180:183], v[34:37], v[50:53]
	ds_read_b128 v[180:183], v117 offset:64
	v_lshlrev_b32_e32 v230, 16, v95
	v_and_b32_e32 v231, 0xffff0000, v95
	s_waitcnt lgkmcnt(13)
	v_mfma_f32_16x16x32_bf16 v[54:57], v[184:187], v[46:49], 0
	ds_read_b128 v[184:187], v117 offset:2304
	v_lshlrev_b32_e32 v232, 16, v92
	v_and_b32_e32 v233, 0xffff0000, v92
	s_waitcnt lgkmcnt(13)
	v_mfma_f32_16x16x32_bf16 v[54:57], v[188:191], v[42:45], v[54:57]
	ds_read_b128 v[188:191], v117 offset:2368
	v_lshlrev_b32_e32 v234, 16, v93
	v_and_b32_e32 v235, 0xffff0000, v93
	s_waitcnt lgkmcnt(13)
	v_mfma_f32_16x16x32_bf16 v[54:57], v[192:195], v[38:41], v[54:57]
	ds_read_b128 v[192:195], v117 offset:4608
	v_lshlrev_b32_e32 v246, 16, v90
	v_and_b32_e32 v247, 0xffff0000, v90
	s_waitcnt lgkmcnt(13)
	v_mfma_f32_16x16x32_bf16 v[54:57], v[196:199], v[34:37], v[54:57]
	ds_read_b128 v[196:199], v117 offset:4672
	v_lshlrev_b32_e32 v248, 16, v91
	v_and_b32_e32 v249, 0xffff0000, v91
	s_waitcnt lgkmcnt(13)
	v_mfma_f32_16x16x32_bf16 v[58:61], v[200:203], v[46:49], 0
	ds_read_b128 v[200:203], v117 offset:6912
	v_sub_f32_e32 v224, v224, v120
	v_sub_f32_e32 v225, v225, v121
	v_sub_f32_e32 v226, v226, v122
	v_sub_f32_e32 v227, v227, v123
	s_waitcnt lgkmcnt(13)
	v_mfma_f32_16x16x32_bf16 v[58:61], v[212:215], v[42:45], v[58:61]
	ds_read_b128 v[212:215], v117 offset:6976
	v_sub_f32_e32 v228, v228, v124
	v_sub_f32_e32 v229, v229, v125
	v_sub_f32_e32 v230, v230, v126
	v_sub_f32_e32 v231, v231, v127
	s_waitcnt lgkmcnt(13)
	v_mfma_f32_16x16x32_bf16 v[58:61], v[216:219], v[38:41], v[58:61]
	ds_read_b128 v[216:219], v118
	v_sub_f32_e32 v232, v232, v128
	v_sub_f32_e32 v233, v233, v129
	v_sub_f32_e32 v234, v234, v130
	v_sub_f32_e32 v235, v235, v131
	s_waitcnt lgkmcnt(13)
	v_mfma_f32_16x16x32_bf16 v[58:61], v[220:223], v[34:37], v[58:61]
	ds_read_b128 v[220:223], v118 offset:64
	v_sub_f32_e32 v246, v246, v132
	v_sub_f32_e32 v247, v247, v133
	v_sub_f32_e32 v248, v248, v134
	v_sub_f32_e32 v249, v249, v135
	s_waitcnt lgkmcnt(13)
	v_mfma_f32_16x16x32_bf16 v[136:139], v[160:163], v[46:49], 0
	ds_read_b128 v[160:163], v118 offset:2304
	v_cvt_pk_bf16_f32 v140, v224, v225
	v_cvt_pk_bf16_f32 v141, v226, v227
	s_waitcnt lgkmcnt(13)
	v_mfma_f32_16x16x32_bf16 v[136:139], v[164:167], v[42:45], v[136:139]
	ds_read_b128 v[164:167], v118 offset:2368
	v_cvt_pk_bf16_f32 v142, v228, v229
	v_cvt_pk_bf16_f32 v143, v230, v231
	s_waitcnt lgkmcnt(13)
	v_mfma_f32_16x16x32_bf16 v[136:139], v[168:171], v[38:41], v[136:139]
	ds_read_b128 v[168:171], v118 offset:4608
	v_cvt_pk_bf16_f32 v144, v232, v233
	v_cvt_pk_bf16_f32 v145, v234, v235
	s_waitcnt lgkmcnt(13)
	v_mfma_f32_16x16x32_bf16 v[136:139], v[172:175], v[34:37], v[136:139]
	ds_read_b128 v[172:175], v118 offset:4672
	v_cvt_pk_bf16_f32 v146, v246, v247
	v_cvt_pk_bf16_f32 v147, v248, v249
	s_waitcnt lgkmcnt(13)
	v_mfma_f32_16x16x32_bf16 v[50:53], v[176:179], v[140:143], v[50:53]
	ds_read_b128 v[176:179], v118 offset:6912
	s_waitcnt lgkmcnt(13)
	v_mfma_f32_16x16x32_bf16 v[50:53], v[180:183], v[144:147], v[50:53]
	ds_read_b128 v[180:183], v118 offset:6976
	s_waitcnt lgkmcnt(13)
	v_mfma_f32_16x16x32_bf16 v[54:57], v[184:187], v[140:143], v[54:57]
	ds_read_b128 v[184:187], v118 offset:9216
	s_waitcnt lgkmcnt(13)
	v_mfma_f32_16x16x32_bf16 v[54:57], v[188:191], v[144:147], v[54:57]
	ds_read_b128 v[188:191], v118 offset:9280
	s_waitcnt lgkmcnt(13)
	v_mfma_f32_16x16x32_bf16 v[58:61], v[192:195], v[140:143], v[58:61]
	ds_read_b128 v[192:195], v118 offset:11520
	s_waitcnt lgkmcnt(13)
	v_mfma_f32_16x16x32_bf16 v[58:61], v[196:199], v[144:147], v[58:61]
	ds_read_b128 v[196:199], v118 offset:11584
	s_waitcnt lgkmcnt(13)
	v_mfma_f32_16x16x32_bf16 v[136:139], v[200:203], v[140:143], v[136:139]
	ds_read_b128 v[200:203], v118 offset:13824
	s_waitcnt lgkmcnt(13)
	v_mfma_f32_16x16x32_bf16 v[136:139], v[212:215], v[144:147], v[136:139]
	ds_read_b128 v[212:215], v118 offset:13888
	s_waitcnt lgkmcnt(13)
	v_mfma_f32_16x16x32_bf16 v[14:17], v[216:219], v[140:143], v[14:17]
	ds_read_b128 v[216:219], v118 offset:16128
	s_waitcnt lgkmcnt(13)
	v_mfma_f32_16x16x32_bf16 v[14:17], v[220:223], v[144:147], v[14:17]
	ds_read_b128 v[220:223], v118 offset:16192
	s_cmp_eq_u32 s18, 0
	s_cbranch_scc1 .Lscan_cp1skipB
	v_add_u32_e32 v0, v108, v107
	ds_read_b128 v[224:227], v0 offset:8192
	v_add_u32_e32 v0, v108, v106
	ds_read_b128 v[228:231], v0 offset:8192
	ds_read_b32 v232, v81 offset:1024
; DI unsigned pack2(float lo, float hi) { f32x2 v = {lo, hi}; bf2_t b = __builtin_convertvector(v, bf2_t); return __builtin_bit_cast(unsigned, b); }
; #define MFMA16(a, b, c) __builtin_amdgcn_mfma_f32_16x16x32_bf16((a), (b), (c), 0, 0, 0)
; DI void gdn_scan_item(const Params& P, int l, int hh, int half, char* smem) {
;     ...
;       { char* so = smem + SCAN_SO + (n & 1) * 8192 + (w * 4) * 512 + lane * 8;
; #pragma unroll
;         for (int it = 0; it < 4; ++it) { u32x2 ob = {pack2(qs[it].x, qs[it].y), pack2(qs[it].z, qs[it].w)}; *(u32x2*)(so + it * 512) = ob; } }
; #pragma unroll
;       for (int t = 0; t < 8; ++t) { St[t] *= gcur;
; #pragma unroll
;         for (int ks = 0; ks < 2; ++ks) { const bf16x8 a = *(const bf16x8*)(sKt + (16 * t + l15) * 144 + 64 * ks + 16 * q4); St[t] = MFMA16(a, vb[ks], St[t]); } }
; #pragma unroll
;       for (int it = 0; it < 4; ++it) uc[it] = un[it];
;       gcur = gn;
;       if (n >= 2) CP_OUT(n - 2);
;       __syncthreads();
;     }
.Lscan_cp1skipB:
	s_waitcnt lgkmcnt(13)
	v_mfma_f32_16x16x32_bf16 v[30:33], v[160:163], v[140:143], v[30:33]
	s_waitcnt lgkmcnt(12)
	v_mfma_f32_16x16x32_bf16 v[30:33], v[164:167], v[144:147], v[30:33]
	s_waitcnt lgkmcnt(11)
	v_mfma_f32_16x16x32_bf16 v[26:29], v[168:171], v[140:143], v[26:29]
	v_cvt_pk_bf16_f32 v236, v50, v51
	v_cvt_pk_bf16_f32 v237, v52, v53
	s_waitcnt lgkmcnt(10)
	v_mfma_f32_16x16x32_bf16 v[26:29], v[172:175], v[144:147], v[26:29]
	v_cvt_pk_bf16_f32 v210, v54, v55
	v_cvt_pk_bf16_f32 v211, v56, v57
	ds_write2st64_b64 v119, v[236:237], v[210:211] offset0:16 offset1:17
	s_waitcnt lgkmcnt(10)
	v_mfma_f32_16x16x32_bf16 v[22:25], v[176:179], v[140:143], v[22:25]
	s_waitcnt lgkmcnt(9)
	v_mfma_f32_16x16x32_bf16 v[22:25], v[180:183], v[144:147], v[22:25]
	s_waitcnt lgkmcnt(8)
	v_mfma_f32_16x16x32_bf16 v[18:21], v[184:187], v[140:143], v[18:21]
	v_cvt_pk_bf16_f32 v250, v58, v59
	v_cvt_pk_bf16_f32 v251, v60, v61
	s_waitcnt lgkmcnt(7)
	v_mfma_f32_16x16x32_bf16 v[18:21], v[188:191], v[144:147], v[18:21]
	v_cvt_pk_bf16_f32 v252, v136, v137
	v_cvt_pk_bf16_f32 v253, v138, v139
	ds_write2st64_b64 v119, v[250:251], v[252:253] offset0:18 offset1:19
	s_waitcnt lgkmcnt(7)
	v_mfma_f32_16x16x32_bf16 v[10:13], v[192:195], v[140:143], v[10:13]
	s_waitcnt lgkmcnt(6)
	v_mfma_f32_16x16x32_bf16 v[10:13], v[196:199], v[144:147], v[10:13]
	s_waitcnt lgkmcnt(5)
	v_mfma_f32_16x16x32_bf16 v[6:9], v[200:203], v[140:143], v[6:9]
	s_waitcnt lgkmcnt(4)
	v_mfma_f32_16x16x32_bf16 v[6:9], v[212:215], v[144:147], v[6:9]
	s_cmp_eq_u32 s18, 0
	s_cbranch_scc1 .Lscan_cp2skipB
	v_add_co_u32_e32 v150, vcc, 0x62a8000, v104
	v_subrev_u32_e32 v0, 64, v205
	v_lshlrev_b64 v[234:235], 5, v[0:1]
	v_addc_co_u32_e32 v151, vcc, 0, v105, vcc
	v_add_co_u32_e32 v154, vcc, 0x62a8000, v102
	v_lshl_add_u64 v[234:235], v[70:71], 0, v[234:235]
	s_waitcnt lgkmcnt(2)
	v_addc_co_u32_e32 v155, vcc, 0, v103, vcc
	global_store_dwordx4 v[150:151], v[224:227], off
	global_store_dwordx4 v[154:155], v[228:231], off
	global_store_dword v[234:235], v232, off
.Lscan_cp2skipB:
	s_waitcnt lgkmcnt(3)
	v_mfma_f32_16x16x32_bf16 v[2:5], v[216:219], v[140:143], v[2:5]
	s_waitcnt lgkmcnt(2)
	v_mfma_f32_16x16x32_bf16 v[2:5], v[220:223], v[144:147], v[2:5]
	s_waitcnt lgkmcnt(0)
	s_barrier
	s_branch .LBB0_664
.Lscan_wA0:
	s_waitcnt vmcnt(0)
	s_branch .Lscan_wA_back
